# weight K-tile L2 prefetch hint before the group seams, issued by waves 1-7 only
# speedup vs baseline: 1.0015x; 1.0015x over previous
; __device__ __forceinline__ unsigned xb_add(unsigned* p, unsigned v) { return __hip_atomic_fetch_add(p, v, __ATOMIC_RELAXED, __HIP_MEMORY_SCOPE_AGENT); }
; #define SEAM(k) do { if (IN(k) && IN((k) + 1)) GRID_SYNC(); } while (0)
; __device__ __forceinline__ void xcd_barrier(const XcdBarrier& b) {
;     asm volatile("s_waitcnt vmcnt(0)" ::: "memory");
;     __syncthreads();
;     if (threadIdx.x == 0) {
;         unsigned* bar = b.bar;
;         __builtin_amdgcn_s_waitcnt(0);
;         unsigned nloc = b.st[0], nx = b.st[1];
;         if (nloc == 0u) { xcd_barrier_complete(bar, b.x, nloc, nx); b.st[0] = nloc; b.st[1] = nx; }
;         const unsigned old = xb_add(&bar[XB_XSUB(b.x)], 1u);
; __global__ void __launch_bounds__(NTHR, 2) mk_fwd(MkArgs a) {
;     ...
;     SEAM(3);
.LBB9_444:
	v_readlane_b32 s97, v251, 39
	s_cmp_gt_i32 s93, 4
	s_cselect_b64 s[0:1], -1, 0
	s_and_b64 s[2:3], s[22:23], s[0:1]
	s_andn2_b64 vcc, exec, s[2:3]
	s_cbranch_vccnz .LBB9_498
	s_waitcnt vmcnt(0)
	s_waitcnt vmcnt(0) lgkmcnt(0)
	s_barrier
	s_cmp_lg_u64 s[80:81], 0
	s_cbranch_scc1 .Lbpf_4
	v_mbcnt_lo_u32_b32 v252, -1, 0
	v_mbcnt_hi_u32_b32 v252, -1, v252
	s_lshr_b32 s98, s97, 6
	s_lshl_b32 s98, s98, 8
	v_lshrrev_b32_e32 v253, 1, v252
	v_and_b32_e32 v252, 1, v252
	v_add_u32_e32 v253, s98, v253
	v_mul_u32_u24_e32 v253, 0x800, v253
	v_lshl_add_u32 v252, v252, 7, v253
	s_add_u32 s98, s90, 0xe500000
	s_addc_u32 s99, s91, 0
	global_load_dword v254, v252, s[98:99]
	v_add_u32_e32 v252, 0x10000, v252
	global_load_dword v254, v252, s[98:99]
	v_add_u32_e32 v252, 0x10000, v252
	global_load_dword v254, v252, s[98:99]
	v_add_u32_e32 v252, 0x10000, v252
	global_load_dword v254, v252, s[98:99]
	v_add_u32_e32 v252, 0x10000, v252
	global_load_dword v254, v252, s[98:99]
	v_add_u32_e32 v252, 0x10000, v252
	global_load_dword v254, v252, s[98:99]
	v_add_u32_e32 v252, 0x10000, v252
	global_load_dword v254, v252, s[98:99]
	v_add_u32_e32 v252, 0x10000, v252
	global_load_dword v254, v252, s[98:99]
.Lbpf_4:
	s_and_saveexec_b64 s[4:5], s[80:81]
	s_cbranch_execz .LBB9_497
	v_mov_b32_e32 v0, 0x24008
	ds_read_b32 v0, v0
	s_waitcnt lgkmcnt(0)
	v_readfirstlane_b32 s98, v0
	s_nop 3
	s_cmp_eq_u32 s98, 1
	s_cbranch_scc0 .Lgb3_orig
	s_cmpk_lg_i32 s94, 0x100
	s_cbranch_scc1 .Lgb3_orig
	s_and_b32 s98, s97, 63
	s_lshl_b32 s98, s98, 2
	s_add_i32 s98, s98, 0x3f00
	v_mov_b32_e32 v0, s98
	v_mov_b32_e32 v1, 1
	global_atomic_add v0, v1, s[90:91]
	buffer_inv sc1

; __device__ __forceinline__ unsigned xb_add(unsigned* p, unsigned v) { return __hip_atomic_fetch_add(p, v, __ATOMIC_RELAXED, __HIP_MEMORY_SCOPE_AGENT); }
; #define SEAM(k) do { if (IN(k) && IN((k) + 1)) GRID_SYNC(); } while (0)
; __device__ __forceinline__ void xcd_barrier(const XcdBarrier& b) {
;     asm volatile("s_waitcnt vmcnt(0)" ::: "memory");
;     __syncthreads();
;     if (threadIdx.x == 0) {
;         unsigned* bar = b.bar;
;         __builtin_amdgcn_s_waitcnt(0);
;         unsigned nloc = b.st[0], nx = b.st[1];
;         if (nloc == 0u) { xcd_barrier_complete(bar, b.x, nloc, nx); b.st[0] = nloc; b.st[1] = nx; }
;         const unsigned old = xb_add(&bar[XB_XSUB(b.x)], 1u);
; __global__ void __launch_bounds__(NTHR, 2) mk_fwd(MkArgs a) {
;     ...
;     SEAM(4);
.LBB9_591:
	s_cmp_gt_i32 s93, 5
	s_cselect_b64 s[0:1], -1, 0
	s_and_b64 s[2:3], s[6:7], s[0:1]
	s_andn2_b64 vcc, exec, s[2:3]
	s_cbranch_vccnz .LBB9_645
	s_waitcnt vmcnt(0)
	s_waitcnt vmcnt(0) lgkmcnt(0)
	s_barrier
	s_cmp_lg_u64 s[80:81], 0
	s_cbranch_scc1 .Lbpf_5
	v_mbcnt_lo_u32_b32 v252, -1, 0
	v_mbcnt_hi_u32_b32 v252, -1, v252
	s_lshr_b32 s98, s97, 6
	s_lshl_b32 s98, s98, 8
	v_lshrrev_b32_e32 v253, 1, v252
	v_and_b32_e32 v252, 1, v252
	v_add_u32_e32 v253, s98, v253
	v_mul_u32_u24_e32 v253, 0x800, v253
	v_lshl_add_u32 v252, v252, 7, v253
	s_add_u32 s98, s90, 0xc00000
	s_addc_u32 s99, s91, 0
	global_load_dword v254, v252, s[98:99]
	v_add_u32_e32 v252, 0x10000, v252
	global_load_dword v254, v252, s[98:99]
	v_add_u32_e32 v252, 0x10000, v252
	global_load_dword v254, v252, s[98:99]
	v_add_u32_e32 v252, 0x10000, v252
	global_load_dword v254, v252, s[98:99]
	v_add_u32_e32 v252, 0x10000, v252
	global_load_dword v254, v252, s[98:99]
	v_add_u32_e32 v252, 0x10000, v252
	global_load_dword v254, v252, s[98:99]
	v_add_u32_e32 v252, 0x10000, v252
	global_load_dword v254, v252, s[98:99]
	v_add_u32_e32 v252, 0x10000, v252
	global_load_dword v254, v252, s[98:99]
.Lbpf_5:
	s_and_saveexec_b64 s[4:5], s[80:81]
	s_cbranch_execz .LBB9_644
	v_mov_b32_e32 v0, 0x24008
	ds_read_b32 v0, v0
	s_waitcnt lgkmcnt(0)
	v_readfirstlane_b32 s98, v0
	s_nop 3
	s_cmp_eq_u32 s98, 1
	s_cbranch_scc0 .Lgb4_orig
	s_and_b32 s98, s97, 63
	s_lshl_b32 s98, s98, 2
	s_add_i32 s98, s98, 0x3d00
	v_mov_b32_e32 v0, s98
	v_mov_b32_e32 v1, 1
	global_atomic_add v0, v1, s[90:91]
	buffer_inv sc1

; __device__ __forceinline__ unsigned xb_add(unsigned* p, unsigned v) { return __hip_atomic_fetch_add(p, v, __ATOMIC_RELAXED, __HIP_MEMORY_SCOPE_AGENT); }
; #define SEAM(k) do { if (IN(k) && IN((k) + 1)) GRID_SYNC(); } while (0)
; __device__ __forceinline__ void xcd_barrier(const XcdBarrier& b) {
;     asm volatile("s_waitcnt vmcnt(0)" ::: "memory");
;     __syncthreads();
;     if (threadIdx.x == 0) {
;         unsigned* bar = b.bar;
;         __builtin_amdgcn_s_waitcnt(0);
;         unsigned nloc = b.st[0], nx = b.st[1];
;         if (nloc == 0u) { xcd_barrier_complete(bar, b.x, nloc, nx); b.st[0] = nloc; b.st[1] = nx; }
;         const unsigned old = xb_add(&bar[XB_XSUB(b.x)], 1u);
; __global__ void __launch_bounds__(NTHR, 2) mk_fwd(MkArgs a) {
;     ...
;     SEAM(6);
.LBB9_777:
	s_cmp_gt_i32 s93, 7
	s_cselect_b64 s[0:1], -1, 0
	s_and_b64 s[2:3], s[4:5], s[0:1]
	s_andn2_b64 vcc, exec, s[2:3]
	s_cbranch_vccnz .LBB9_831
	s_waitcnt vmcnt(0)
	s_waitcnt vmcnt(0) lgkmcnt(0)
	s_barrier
	s_cmp_lg_u64 s[80:81], 0
	s_cbranch_scc1 .Lbpf_7
	v_mbcnt_lo_u32_b32 v252, -1, 0
	v_mbcnt_hi_u32_b32 v252, -1, v252
	s_lshr_b32 s98, s97, 6
	s_lshl_b32 s98, s98, 8
	v_lshrrev_b32_e32 v253, 1, v252
	v_and_b32_e32 v252, 1, v252
	v_add_u32_e32 v253, s98, v253
	v_mul_u32_u24_e32 v253, 0x1600, v253
	v_lshl_add_u32 v252, v252, 7, v253
	s_add_u32 s98, s90, 0x1900000
	s_addc_u32 s99, s91, 0
	global_load_dword v254, v252, s[98:99]
	v_add_u32_e32 v252, 0x2c000, v252
	global_load_dword v254, v252, s[98:99]
	v_add_u32_e32 v252, 0x2c000, v252
	global_load_dword v254, v252, s[98:99]
	v_add_u32_e32 v252, 0x2c000, v252
	global_load_dword v254, v252, s[98:99]
	v_add_u32_e32 v252, 0x2c000, v252
	global_load_dword v254, v252, s[98:99]
	v_add_u32_e32 v252, 0x2c000, v252
	global_load_dword v254, v252, s[98:99]
	v_add_u32_e32 v252, 0x2c000, v252
	global_load_dword v254, v252, s[98:99]
	v_add_u32_e32 v252, 0x2c000, v252
	global_load_dword v254, v252, s[98:99]
.Lbpf_7:
	s_and_saveexec_b64 s[4:5], s[80:81]
	s_cbranch_execz .LBB9_830
	v_mov_b32_e32 v0, 0x24008
	ds_read_b32 v0, v0
	s_waitcnt lgkmcnt(0)
	v_readfirstlane_b32 s98, v0
	s_nop 3
	s_cmp_eq_u32 s98, 1
	s_cbranch_scc0 .Lgb6_orig
	s_and_b32 s98, s97, 63
	s_lshl_b32 s98, s98, 2
	s_add_i32 s98, s98, 0x3e00
	v_mov_b32_e32 v0, s98
	v_mov_b32_e32 v1, 1
	global_atomic_add v0, v1, s[90:91]
	buffer_inv sc1
